# prologue wave reorder with odd waves (instead of waves 4-7) as the late half
# baseline (speedup 1.0000x reference)
; DEVI const float* IN(int i) { return *(const float* const __attribute__((address_space(4)))*)(kargs() + 8 * i); }
; DEVI void prologue(int wv, LAS unsigned char* lds) {
;     ...
;     for (int it = gw; it < 2 * I_L; it += NGW) {
;         const int l = it / I_L; int r = it % I_L;
;         unsigned char* wl = ws + O_W + (size_t)l * W_LAYER;
;         if (r < I_IN) { const int kb = r / 101, nb = r % 101, n0 = nb * 32;
;             const int d0 = n0 < 384 ? n0 : n0 < 640 ? 512 + (n0 - 384) : n0 < 672 ? 384 + (n0 - 640) : n0 < 1184 ? 768 + (n0 - 672) : n0 < 2208 ? 1280 + (n0 - 1184) : 2304 + (n0 - 2208);
;             tr_item(IN(6) + (size_t)l * 1024 * 3232, 3232, 1024, IN(5) + l * 1024, (bf16_t*)(wl + W_IN), d0, scr, kb * 64, n0, lane); continue; }
;         r -= I_IN;
;         if (r < I_UQ) { const int kb = r / 24, nb = r % 24, n0 = nb * 32, hd = n0 / 96, dim0 = n0 % 96;
;             const int d0 = dim0 < 64 ? 256 * (hd >> 2) + 128 * (dim0 >> 5) + 32 * (hd & 3) : 512 + 128 * (hd >> 2) + 32 * (hd & 3);
;             tr_item(IN(9) + (size_t)l * 384 * 768, 768, 384, IN(7) + l * 384, (bf16_t*)(wl + W_UQ), d0, scr, kb * 64, n0, lane); continue; }
;         r -= I_UQ;
;         if (r < 2 * I_KV) { const int fold = r < I_KV; if (!fold) r -= I_KV;
;             const int kb = r / 32, nb = r % 32, n0 = nb * 32, hd = n0 / 128, dim0 = n0 % 128;
;             const bool isk = dim0 < 64;
;             const int d0 = isk ? 256 * (hd >> 2) + 128 * (dim0 >> 5) + 32 * (hd & 3) : hd * 64 + (dim0 - 64);
;             bf16_t* dst = (bf16_t*)(wl + (fold ? (isk ? W_K : W_V) : (isk ? W_KC : W_VC)));
;             tr_item(IN(10) + (size_t)l * 256 * 1024, 1024, 256, fold ? IN(8) + l * 256 : nullptr, dst, d0, scr, kb * 64, n0, lane); continue; }
;         r -= 2 * I_KV;
;         if (r < I_A) { tr_item(IN(13) + (size_t)l * 512 * 1024, 1024, 512, nullptr, (bf16_t*)(wl + W_A), (r % 32) * 32, scr, (r / 32) * 64, (r % 32) * 32, lane); continue; }
;         r -= I_A;
;         if (r < I_O) { tr_item(IN(17) + (size_t)l * 1024 * 1024, 1024, 1024, nullptr, (bf16_t*)(wl + W_O), (r % 32) * 32, scr, (r / 32) * 64, (r % 32) * 32, lane); continue; }
;         r -= I_O;
;         if (r < I_UP) { tr_item(IN(19) + (size_t)l * 1024 * 4096, 4096, 1024, IN(18) + l * 1024, (bf16_t*)(wl + W_UP), (r % 128) * 32, scr, (r / 128) * 64, (r % 128) * 32, lane); continue; }
;         r -= I_UP;
.LBB0_331:
	s_or_b64 exec, exec, s[8:9]
	s_mov_b32 s53, 0
	s_bitcmp1_b32 s33, 0
	s_cbranch_scc1 .Lpro_c

; DEVI const float* IN(int i) { return *(const float* const __attribute__((address_space(4)))*)(kargs() + 8 * i); }
; DEVI void prologue(int wv, LAS unsigned char* lds) {
;     ...
;     for (int it = gw; it < 2 * I_L; it += NGW) {
;         const int l = it / I_L; int r = it % I_L;
;         unsigned char* wl = ws + O_W + (size_t)l * W_LAYER;
;         if (r < I_IN) { const int kb = r / 101, nb = r % 101, n0 = nb * 32;
;             const int d0 = n0 < 384 ? n0 : n0 < 640 ? 512 + (n0 - 384) : n0 < 672 ? 384 + (n0 - 640) : n0 < 1184 ? 768 + (n0 - 672) : n0 < 2208 ? 1280 + (n0 - 1184) : 2304 + (n0 - 2208);
;             tr_item(IN(6) + (size_t)l * 1024 * 3232, 3232, 1024, IN(5) + l * 1024, (bf16_t*)(wl + W_IN), d0, scr, kb * 64, n0, lane); continue; }
;         r -= I_IN;
;         if (r < I_UQ) { const int kb = r / 24, nb = r % 24, n0 = nb * 32, hd = n0 / 96, dim0 = n0 % 96;
;             const int d0 = dim0 < 64 ? 256 * (hd >> 2) + 128 * (dim0 >> 5) + 32 * (hd & 3) : 512 + 128 * (hd >> 2) + 32 * (hd & 3);
;             tr_item(IN(9) + (size_t)l * 384 * 768, 768, 384, IN(7) + l * 384, (bf16_t*)(wl + W_UQ), d0, scr, kb * 64, n0, lane); continue; }
;         r -= I_UQ;
;         if (r < 2 * I_KV) { const int fold = r < I_KV; if (!fold) r -= I_KV;
;             const int kb = r / 32, nb = r % 32, n0 = nb * 32, hd = n0 / 128, dim0 = n0 % 128;
;             const bool isk = dim0 < 64;
;             const int d0 = isk ? 256 * (hd >> 2) + 128 * (dim0 >> 5) + 32 * (hd & 3) : hd * 64 + (dim0 - 64);
;             bf16_t* dst = (bf16_t*)(wl + (fold ? (isk ? W_K : W_V) : (isk ? W_KC : W_VC)));
;             tr_item(IN(10) + (size_t)l * 256 * 1024, 1024, 256, fold ? IN(8) + l * 256 : nullptr, dst, d0, scr, kb * 64, n0, lane); continue; }
;         r -= 2 * I_KV;
;         if (r < I_A) { tr_item(IN(13) + (size_t)l * 512 * 1024, 1024, 512, nullptr, (bf16_t*)(wl + W_A), (r % 32) * 32, scr, (r / 32) * 64, (r % 32) * 32, lane); continue; }
;         r -= I_A;
;         if (r < I_O) { tr_item(IN(17) + (size_t)l * 1024 * 1024, 1024, 1024, nullptr, (bf16_t*)(wl + W_O), (r % 32) * 32, scr, (r / 32) * 64, (r % 32) * 32, lane); continue; }
;         r -= I_O;
;         if (r < I_UP) { tr_item(IN(19) + (size_t)l * 1024 * 4096, 4096, 1024, IN(18) + l * 1024, (bf16_t*)(wl + W_UP), (r % 128) * 32, scr, (r / 128) * 64, (r % 128) * 32, lane); continue; }
;         r -= I_UP;
.LBB0_359:
	s_bitcmp1_b32 s33, 0
	s_cbranch_scc0 .Lpro_d
	s_cmp_lg_u32 s53, 0
	s_cbranch_scc1 .Lpro_d
	s_mov_b32 s53, 1
	s_branch .Lpro_b
